# adds: GEMM1 K-loop first trip peeled with C=0 (no accumulator zeroing v_movs); conv-weight staging moved behind first tile loads
# speedup vs baseline: 1.4804x; 1.0028x over previous
.LBB0_619:
	s_ashr_i32 s39, s38, 31
	s_lshl_b64 s[2:3], s[38:39], 19
	s_add_u32 s40, s58, s2
	s_addc_u32 s41, s59, s3
	s_and_b64 s[2:3], s[36:37], exec
	s_cselect_b32 s11, s41, s31
	s_cselect_b32 s18, s40, s30
	s_ashr_i32 s13, s12, 31
	s_lshl_b64 s[2:3], s[12:13], 19
	s_add_u32 s42, s6, s2
	s_addc_u32 s43, s7, s3
	s_and_b64 s[2:3], s[36:37], exec
	s_cselect_b32 s13, s43, s17
	s_cselect_b32 s19, s42, s16
	s_add_u32 s30, s30, 0x40080
	s_addc_u32 s31, s31, 0
	s_add_u32 s28, s16, 0x100
	s_addc_u32 s29, s17, 0
	s_mov_b32 s39, -2
	s_add_u32 s2, s30, 0xfffc0080
	s_addc_u32 s3, s31, -1
	s_add_i32 s94, 32, 0x10000
	v_add_u32_e32 v131, s94, v145
	ds_read_b128 v[170:173], v131
	ds_read_b128 v[174:177], v131 offset:1024
	ds_read_b128 v[182:185], v131 offset:2048
	ds_read_b128 v[186:189], v131 offset:3072
	s_cmp_eq_u32 s39, 12
	s_cselect_b32 s3, s11, s3
	s_cselect_b32 s2, s18, s2
	s_cselect_b32 s17, s13, s29
	s_cselect_b32 s16, s19, s28
	v_lshl_add_u64 v[132:133], s[30:31], 0, v[140:141]
	s_add_i32 m0, s35, 0xc000
	ds_read_b128 v[190:193], v151
	ds_read_b128 v[194:197], v151 offset:1024
	ds_read_b128 v[198:201], v151 offset:2048
	ds_read_b128 v[202:205], v151 offset:3072
	ds_read_b128 v[206:209], v151 offset:4096
	ds_read_b128 v[210:213], v151 offset:5120
	ds_read_b128 v[214:217], v151 offset:6144
	ds_read_b128 v[218:221], v151 offset:7168
	global_load_lds_dwordx4 v[132:133], off
	v_lshl_add_u64 v[132:133], s[30:31], 0, v[142:143]
	s_add_i32 m0, s35, 0xe000
	s_nop 0
	global_load_lds_dwordx4 v[132:133], off
	s_waitcnt lgkmcnt(8)
	s_barrier
	s_waitcnt lgkmcnt(0)
	s_waitcnt lgkmcnt(0)
	v_mfma_f32_16x16x32_bf16 v[126:129], v[170:173], v[190:193], 0
	v_mfma_f32_16x16x32_bf16 v[122:125], v[182:185], v[190:193], 0
	v_mfma_f32_16x16x32_bf16 v[110:113], v[170:173], v[198:201], 0
	v_mfma_f32_16x16x32_bf16 v[106:109], v[182:185], v[198:201], 0
	v_mfma_f32_16x16x32_bf16 v[94:97], v[170:173], v[206:209], 0
	v_mfma_f32_16x16x32_bf16 v[90:93], v[182:185], v[206:209], 0
	v_mfma_f32_16x16x32_bf16 v[78:81], v[170:173], v[214:217], 0
	v_mfma_f32_16x16x32_bf16 v[74:77], v[182:185], v[214:217], 0
	v_mfma_f32_16x16x32_bf16 v[126:129], v[174:177], v[194:197], v[126:129]
	v_mfma_f32_16x16x32_bf16 v[122:125], v[186:189], v[194:197], v[122:125]
	v_mfma_f32_16x16x32_bf16 v[110:113], v[174:177], v[202:205], v[110:113]
	v_mfma_f32_16x16x32_bf16 v[106:109], v[186:189], v[202:205], v[106:109]
	v_mfma_f32_16x16x32_bf16 v[94:97], v[174:177], v[210:213], v[94:97]
	v_mfma_f32_16x16x32_bf16 v[90:93], v[186:189], v[210:213], v[90:93]
	v_mfma_f32_16x16x32_bf16 v[78:81], v[174:177], v[218:221], v[78:81]
	v_mfma_f32_16x16x32_bf16 v[74:77], v[186:189], v[218:221], v[74:77]
	s_barrier
	s_add_i32 vcc_lo, 32, 0x14000
	s_add_i32 s94, s94, s5
	v_add_u32_e32 v131, vcc_lo, v145
	v_lshl_add_u64 v[132:133], s[16:17], 0, v[154:155]
	s_mov_b32 m0, s94
	ds_read_b128 v[222:225], v131
	ds_read_b128 v[226:229], v131 offset:1024
	ds_read_b128 v[230:233], v131 offset:2048
	ds_read_b128 v[234:237], v131 offset:3072
	global_load_lds_dwordx4 v[132:133], off
	v_lshl_add_u64 v[178:179], s[16:17], 0, v[138:139]
	s_add_i32 m0, s94, 0x2000
	s_nop 0
	global_load_lds_dwordx4 v[178:179], off
	s_barrier
	s_waitcnt lgkmcnt(0)
	s_waitcnt lgkmcnt(0)
	v_mfma_f32_16x16x32_bf16 v[118:121], v[222:225], v[190:193], 0
	v_mfma_f32_16x16x32_bf16 v[114:117], v[230:233], v[190:193], 0
	v_mfma_f32_16x16x32_bf16 v[102:105], v[222:225], v[198:201], 0
	v_mfma_f32_16x16x32_bf16 v[98:101], v[230:233], v[198:201], 0
	v_mfma_f32_16x16x32_bf16 v[86:89], v[222:225], v[206:209], 0
	v_mfma_f32_16x16x32_bf16 v[82:85], v[230:233], v[206:209], 0
	v_mfma_f32_16x16x32_bf16 v[70:73], v[222:225], v[214:217], 0
	v_mfma_f32_16x16x32_bf16 v[66:69], v[230:233], v[214:217], 0
	v_mfma_f32_16x16x32_bf16 v[118:121], v[226:229], v[194:197], v[118:121]
	v_mfma_f32_16x16x32_bf16 v[114:117], v[234:237], v[194:197], v[114:117]
	v_mfma_f32_16x16x32_bf16 v[102:105], v[226:229], v[202:205], v[102:105]
	v_mfma_f32_16x16x32_bf16 v[98:101], v[234:237], v[202:205], v[98:101]
	v_mfma_f32_16x16x32_bf16 v[86:89], v[226:229], v[210:213], v[86:89]
	v_mfma_f32_16x16x32_bf16 v[82:85], v[234:237], v[210:213], v[82:85]
	v_mfma_f32_16x16x32_bf16 v[70:73], v[226:229], v[218:221], v[70:73]
	v_mfma_f32_16x16x32_bf16 v[66:69], v[234:237], v[218:221], v[66:69]
	s_mov_b32 m0, s35
	v_lshl_add_u64 v[238:239], s[2:3], 0, v[134:135]
	s_barrier
	ds_read_b128 v[190:193], v151 offset:16384
	ds_read_b128 v[194:197], v151 offset:17408
	ds_read_b128 v[198:201], v151 offset:18432
	ds_read_b128 v[202:205], v151 offset:19456
	ds_read_b128 v[206:209], v151 offset:20480
	ds_read_b128 v[210:213], v151 offset:21504
	ds_read_b128 v[214:217], v151 offset:22528
	ds_read_b128 v[218:221], v151 offset:23552
	global_load_lds_dwordx4 v[238:239], off
	v_lshl_add_u64 v[240:241], s[2:3], 0, v[136:137]
	s_mov_b32 m0, s14
	s_nop 0
	global_load_lds_dwordx4 v[240:241], off
	s_barrier
	s_waitcnt lgkmcnt(0)
	s_waitcnt lgkmcnt(0)
	v_mfma_f32_16x16x32_bf16 v[62:65], v[170:173], v[190:193], 0
	v_mfma_f32_16x16x32_bf16 v[58:61], v[182:185], v[190:193], 0
	v_mfma_f32_16x16x32_bf16 v[46:49], v[170:173], v[198:201], 0
	v_mfma_f32_16x16x32_bf16 v[42:45], v[182:185], v[198:201], 0
	v_mfma_f32_16x16x32_bf16 v[30:33], v[170:173], v[206:209], 0
	v_mfma_f32_16x16x32_bf16 v[26:29], v[182:185], v[206:209], 0
	v_mfma_f32_16x16x32_bf16 v[14:17], v[170:173], v[214:217], 0
	v_mfma_f32_16x16x32_bf16 v[10:13], v[182:185], v[214:217], 0
	v_mfma_f32_16x16x32_bf16 v[62:65], v[174:177], v[194:197], v[62:65]
	v_mfma_f32_16x16x32_bf16 v[58:61], v[186:189], v[194:197], v[58:61]
	v_mfma_f32_16x16x32_bf16 v[46:49], v[174:177], v[202:205], v[46:49]
	v_mfma_f32_16x16x32_bf16 v[42:45], v[186:189], v[202:205], v[42:45]
	v_mfma_f32_16x16x32_bf16 v[30:33], v[174:177], v[210:213], v[30:33]
	v_mfma_f32_16x16x32_bf16 v[26:29], v[186:189], v[210:213], v[26:29]
	v_mfma_f32_16x16x32_bf16 v[14:17], v[174:177], v[218:221], v[14:17]
	v_mfma_f32_16x16x32_bf16 v[10:13], v[186:189], v[218:221], v[10:13]
	s_barrier
	s_add_u32 s94, s16, 0x40000
	s_addc_u32 s95, s17, 0
	s_add_i32 vcc_lo, vcc_lo, s5
	v_lshl_add_u64 v[170:171], s[94:95], 0, v[154:155]
	s_mov_b32 m0, vcc_lo
	s_nop 0
	global_load_lds_dwordx4 v[170:171], off
	v_lshl_add_u64 v[170:171], s[94:95], 0, v[138:139]
	s_add_i32 m0, vcc_lo, 0x2000
	s_nop 0
	global_load_lds_dwordx4 v[170:171], off
	s_waitcnt vmcnt(6)
	s_barrier
	v_mfma_f32_16x16x32_bf16 v[54:57], v[222:225], v[190:193], 0
	v_mfma_f32_16x16x32_bf16 v[50:53], v[230:233], v[190:193], 0
	v_mfma_f32_16x16x32_bf16 v[38:41], v[222:225], v[198:201], 0
	v_mfma_f32_16x16x32_bf16 v[34:37], v[230:233], v[198:201], 0
	v_mfma_f32_16x16x32_bf16 v[22:25], v[222:225], v[206:209], 0
	v_mfma_f32_16x16x32_bf16 v[18:21], v[230:233], v[206:209], 0
	v_mfma_f32_16x16x32_bf16 v[6:9], v[222:225], v[214:217], 0
	v_mfma_f32_16x16x32_bf16 v[2:5], v[230:233], v[214:217], 0
	v_mfma_f32_16x16x32_bf16 v[54:57], v[226:229], v[194:197], v[54:57]
	v_mfma_f32_16x16x32_bf16 v[50:53], v[234:237], v[194:197], v[50:53]
	v_mfma_f32_16x16x32_bf16 v[38:41], v[226:229], v[202:205], v[38:41]
	v_mfma_f32_16x16x32_bf16 v[34:37], v[234:237], v[202:205], v[34:37]
	v_mfma_f32_16x16x32_bf16 v[22:25], v[226:229], v[210:213], v[22:25]
	v_mfma_f32_16x16x32_bf16 v[18:21], v[234:237], v[210:213], v[18:21]
	v_mfma_f32_16x16x32_bf16 v[6:9], v[226:229], v[218:221], v[6:9]
	v_mfma_f32_16x16x32_bf16 v[2:5], v[234:237], v[218:221], v[2:5]
	s_add_i32 s94, 32, 0x18000
	v_add_u32_e32 v131, s94, v145
	s_barrier
	ds_read_b128 v[170:173], v131
	ds_read_b128 v[174:177], v131 offset:1024
	ds_read_b128 v[182:185], v131 offset:2048
	ds_read_b128 v[186:189], v131 offset:3072
	s_add_u32 s2, s2, 0x40000
	s_addc_u32 s3, s3, 0
	s_mov_b32 m0, s4
	v_lshl_add_u64 v[222:223], s[2:3], 0, v[134:135]
	ds_read_b128 v[190:193], v151 offset:32768
	ds_read_b128 v[194:197], v151 offset:33792
	ds_read_b128 v[198:201], v151 offset:34816
	ds_read_b128 v[202:205], v151 offset:35840
	ds_read_b128 v[206:209], v151 offset:36864
	ds_read_b128 v[210:213], v151 offset:37888
	ds_read_b128 v[214:217], v151 offset:38912
	ds_read_b128 v[218:221], v151 offset:39936
	global_load_lds_dwordx4 v[222:223], off
	v_lshl_add_u64 v[222:223], s[2:3], 0, v[136:137]
	s_mov_b32 m0, s20
	s_nop 0
	global_load_lds_dwordx4 v[222:223], off
	s_waitcnt lgkmcnt(8)
	s_barrier
	s_waitcnt lgkmcnt(0)
	s_waitcnt lgkmcnt(0)
	v_mfma_f32_16x16x32_bf16 v[126:129], v[170:173], v[190:193], v[126:129]
	v_mfma_f32_16x16x32_bf16 v[122:125], v[182:185], v[190:193], v[122:125]
	v_mfma_f32_16x16x32_bf16 v[110:113], v[170:173], v[198:201], v[110:113]
	v_mfma_f32_16x16x32_bf16 v[106:109], v[182:185], v[198:201], v[106:109]
	v_mfma_f32_16x16x32_bf16 v[94:97], v[170:173], v[206:209], v[94:97]
	v_mfma_f32_16x16x32_bf16 v[90:93], v[182:185], v[206:209], v[90:93]
	v_mfma_f32_16x16x32_bf16 v[78:81], v[170:173], v[214:217], v[78:81]
	v_mfma_f32_16x16x32_bf16 v[74:77], v[182:185], v[214:217], v[74:77]
	v_mfma_f32_16x16x32_bf16 v[126:129], v[174:177], v[194:197], v[126:129]
	v_mfma_f32_16x16x32_bf16 v[122:125], v[186:189], v[194:197], v[122:125]
	v_mfma_f32_16x16x32_bf16 v[110:113], v[174:177], v[202:205], v[110:113]
	v_mfma_f32_16x16x32_bf16 v[106:109], v[186:189], v[202:205], v[106:109]
	v_mfma_f32_16x16x32_bf16 v[94:97], v[174:177], v[210:213], v[94:97]
	v_mfma_f32_16x16x32_bf16 v[90:93], v[186:189], v[210:213], v[90:93]
	v_mfma_f32_16x16x32_bf16 v[78:81], v[174:177], v[218:221], v[78:81]
	v_mfma_f32_16x16x32_bf16 v[74:77], v[186:189], v[218:221], v[74:77]
	s_barrier
	s_add_i32 s95, 32, 0x1c000
	s_add_i32 s2, s94, s5
	v_add_u32_e32 v131, s95, v145
	v_lshl_add_u64 v[132:133], v[132:133], 0, s[44:45]
	s_mov_b32 m0, s2
	ds_read_b128 v[222:225], v131
	ds_read_b128 v[226:229], v131 offset:1024
	ds_read_b128 v[230:233], v131 offset:2048
	ds_read_b128 v[234:237], v131 offset:3072
	global_load_lds_dwordx4 v[132:133], off
	v_lshl_add_u64 v[132:133], v[178:179], 0, s[44:45]
	s_add_i32 m0, s2, 0x2000
	s_nop 0
	global_load_lds_dwordx4 v[132:133], off
	s_barrier
	s_waitcnt lgkmcnt(0)
	s_waitcnt lgkmcnt(0)
	v_mfma_f32_16x16x32_bf16 v[118:121], v[222:225], v[190:193], v[118:121]
	v_mfma_f32_16x16x32_bf16 v[114:117], v[230:233], v[190:193], v[114:117]
	v_mfma_f32_16x16x32_bf16 v[102:105], v[222:225], v[198:201], v[102:105]
	v_mfma_f32_16x16x32_bf16 v[98:101], v[230:233], v[198:201], v[98:101]
	v_mfma_f32_16x16x32_bf16 v[86:89], v[222:225], v[206:209], v[86:89]
	v_mfma_f32_16x16x32_bf16 v[82:85], v[230:233], v[206:209], v[82:85]
	v_mfma_f32_16x16x32_bf16 v[70:73], v[222:225], v[214:217], v[70:73]
	v_mfma_f32_16x16x32_bf16 v[66:69], v[230:233], v[214:217], v[66:69]
	v_mfma_f32_16x16x32_bf16 v[118:121], v[226:229], v[194:197], v[118:121]
	v_mfma_f32_16x16x32_bf16 v[114:117], v[234:237], v[194:197], v[114:117]
	v_mfma_f32_16x16x32_bf16 v[102:105], v[226:229], v[202:205], v[102:105]
	v_mfma_f32_16x16x32_bf16 v[98:101], v[234:237], v[202:205], v[98:101]
	v_mfma_f32_16x16x32_bf16 v[86:89], v[226:229], v[210:213], v[86:89]
	v_mfma_f32_16x16x32_bf16 v[82:85], v[234:237], v[210:213], v[82:85]
	v_mfma_f32_16x16x32_bf16 v[70:73], v[226:229], v[218:221], v[70:73]
	v_mfma_f32_16x16x32_bf16 v[66:69], v[234:237], v[218:221], v[66:69]
	s_mov_b32 m0, s21
	v_lshl_add_u64 v[132:133], v[238:239], 0, s[44:45]
	s_barrier
	ds_read_b128 v[190:193], v151 offset:49152
	ds_read_b128 v[194:197], v151 offset:50176
	ds_read_b128 v[198:201], v151 offset:51200
	ds_read_b128 v[202:205], v151 offset:52224
	ds_read_b128 v[206:209], v151 offset:53248
	ds_read_b128 v[210:213], v151 offset:54272
	ds_read_b128 v[214:217], v151 offset:55296
	ds_read_b128 v[218:221], v151 offset:56320
	global_load_lds_dwordx4 v[132:133], off
	v_lshl_add_u64 v[132:133], v[240:241], 0, s[44:45]
	s_mov_b32 m0, s22
	s_nop 0
	global_load_lds_dwordx4 v[132:133], off
	s_barrier
	s_waitcnt lgkmcnt(0)
	s_waitcnt lgkmcnt(0)
	v_mfma_f32_16x16x32_bf16 v[62:65], v[170:173], v[190:193], v[62:65]
	v_mfma_f32_16x16x32_bf16 v[58:61], v[182:185], v[190:193], v[58:61]
	v_mfma_f32_16x16x32_bf16 v[46:49], v[170:173], v[198:201], v[46:49]
	v_mfma_f32_16x16x32_bf16 v[42:45], v[182:185], v[198:201], v[42:45]
	v_mfma_f32_16x16x32_bf16 v[30:33], v[170:173], v[206:209], v[30:33]
	v_mfma_f32_16x16x32_bf16 v[26:29], v[182:185], v[206:209], v[26:29]
	v_mfma_f32_16x16x32_bf16 v[14:17], v[170:173], v[214:217], v[14:17]
	v_mfma_f32_16x16x32_bf16 v[10:13], v[182:185], v[214:217], v[10:13]
	v_mfma_f32_16x16x32_bf16 v[62:65], v[174:177], v[194:197], v[62:65]
	v_mfma_f32_16x16x32_bf16 v[58:61], v[186:189], v[194:197], v[58:61]
	v_mfma_f32_16x16x32_bf16 v[46:49], v[174:177], v[202:205], v[46:49]
	v_mfma_f32_16x16x32_bf16 v[42:45], v[186:189], v[202:205], v[42:45]
	v_mfma_f32_16x16x32_bf16 v[30:33], v[174:177], v[210:213], v[30:33]
	v_mfma_f32_16x16x32_bf16 v[26:29], v[186:189], v[210:213], v[26:29]
	v_mfma_f32_16x16x32_bf16 v[14:17], v[174:177], v[218:221], v[14:17]
	v_mfma_f32_16x16x32_bf16 v[10:13], v[186:189], v[218:221], v[10:13]
	s_barrier
	s_add_u32 s2, s16, 0x40080
	s_addc_u32 s3, s17, 0
	s_add_i32 s16, s95, s5
	v_lshl_add_u64 v[132:133], s[2:3], 0, v[154:155]
	s_mov_b32 m0, s16
	s_nop 0
	global_load_lds_dwordx4 v[132:133], off
	v_lshl_add_u64 v[132:133], s[2:3], 0, v[138:139]
	s_add_i32 m0, s16, 0x2000
	s_nop 0
	global_load_lds_dwordx4 v[132:133], off
	s_waitcnt vmcnt(6)
	s_barrier
	v_mfma_f32_16x16x32_bf16 v[54:57], v[222:225], v[190:193], v[54:57]
	v_mfma_f32_16x16x32_bf16 v[50:53], v[230:233], v[190:193], v[50:53]
	v_mfma_f32_16x16x32_bf16 v[38:41], v[222:225], v[198:201], v[38:41]
	v_mfma_f32_16x16x32_bf16 v[34:37], v[230:233], v[198:201], v[34:37]
	v_mfma_f32_16x16x32_bf16 v[22:25], v[222:225], v[206:209], v[22:25]
	v_mfma_f32_16x16x32_bf16 v[18:21], v[230:233], v[206:209], v[18:21]
	v_mfma_f32_16x16x32_bf16 v[6:9], v[222:225], v[214:217], v[6:9]
	v_mfma_f32_16x16x32_bf16 v[2:5], v[230:233], v[214:217], v[2:5]
	v_mfma_f32_16x16x32_bf16 v[54:57], v[226:229], v[194:197], v[54:57]
	v_mfma_f32_16x16x32_bf16 v[50:53], v[234:237], v[194:197], v[50:53]
	v_mfma_f32_16x16x32_bf16 v[38:41], v[226:229], v[202:205], v[38:41]
	v_mfma_f32_16x16x32_bf16 v[34:37], v[234:237], v[202:205], v[34:37]
	v_mfma_f32_16x16x32_bf16 v[22:25], v[226:229], v[210:213], v[22:25]
	v_mfma_f32_16x16x32_bf16 v[18:21], v[234:237], v[210:213], v[18:21]
	v_mfma_f32_16x16x32_bf16 v[6:9], v[226:229], v[218:221], v[6:9]
	v_mfma_f32_16x16x32_bf16 v[2:5], v[234:237], v[218:221], v[2:5]
	s_add_i32 s39, s39, 2
	s_add_u32 s30, s30, 0x100
	s_addc_u32 s31, s31, 0
	s_add_u32 s28, s28, 0x100
	s_addc_u32 s29, s29, 0
	s_cmp_gt_u32 s39, 13
	s_barrier

.LBB0_743:
.LBB0_748:
	v_readlane_b32 s0, v242, 0
	v_readlane_b32 s0, v242, 40
	v_readlane_b32 s1, v242, 1
	s_mulk_i32 s0, 0x2e80
	v_writelane_b32 v242, s0, 0
	v_readlane_b32 s4, v243, 18
	v_readlane_b32 s5, v243, 19
	v_writelane_b32 v242, s1, 1
	s_lshl_b64 s[0:1], s[0:1], 2
	s_add_u32 s0, s76, s0
	s_addc_u32 s1, s77, s1
	s_and_b64 vcc, exec, s[4:5]
	v_readlane_b32 s4, v243, 20
	v_readlane_b32 s5, v243, 21
	s_mov_b64 s[2:3], -1
	s_nop 0
	v_cndmask_b32_e64 v2, 0, 1, s[4:5]
	v_cmp_ne_u32_e64 s[38:39], 1, v2
	s_cbranch_vccz .LBB0_776
	s_and_b64 vcc, exec, s[38:39]
	s_waitcnt vmcnt(0)
	v_mov_b32_e32 v5, v69
	v_mov_b32_e32 v4, v68
	v_mov_b32_e32 v3, v67
	v_mov_b32_e32 v2, v66
	v_mov_b32_e32 v9, v73
	v_mov_b32_e32 v8, v72
	v_mov_b32_e32 v7, v71
	v_mov_b32_e32 v6, v70
	v_mov_b32_e32 v13, v81
	v_mov_b32_e32 v12, v80
	v_mov_b32_e32 v11, v79
	v_mov_b32_e32 v10, v78
	v_mov_b32_e32 v17, v77
	v_mov_b32_e32 v16, v76
	v_mov_b32_e32 v15, v75
	v_mov_b32_e32 v14, v74
	v_mov_b32_e32 v21, v89
	v_mov_b32_e32 v20, v88
	v_mov_b32_e32 v19, v87
	v_mov_b32_e32 v18, v86
	v_mov_b32_e32 v25, v85
	v_mov_b32_e32 v24, v84
	v_mov_b32_e32 v23, v83
	v_mov_b32_e32 v22, v82
	s_cbranch_vccnz .LBB0_775
	v_mov_b32_e32 v26, v0
	s_movk_i32 s2, 0xba0
	v_mov_b32_e32 v6, 0
	v_cmp_gt_i32_e32 vcc, s2, v26
	v_mov_b32_e32 v2, 0
	v_mov_b32_e32 v3, 0
	v_mov_b32_e32 v4, 0
	v_mov_b32_e32 v5, 0
	s_and_saveexec_b64 s[2:3], vcc
	s_cbranch_execz .LBB0_754
	s_mov_b32 s4, 0x2aaaaaab
	v_mul_hi_i32 v2, v26, s4
	v_lshrrev_b32_e32 v3, 31, v2
	v_ashrrev_i32_e32 v2, 3, v2
	v_add_u32_e32 v7, v2, v3
	v_subrev_u32_e32 v8, 30, v7
	v_readlane_b32 s4, v243, 26
	v_mov_b32_e32 v5, 0
	v_mov_b32_e32 v4, 0
	v_cmp_lt_i32_e32 vcc, s4, v8
	v_mov_b32_e32 v3, 0
	v_mov_b32_e32 v2, 0
	s_and_saveexec_b64 s[10:11], vcc
	s_cbranch_execz .LBB0_753
	v_readlane_b32 s4, v243, 25
	s_nop 1
	v_add_u32_e32 v2, s4, v8
	s_movk_i32 s4, 0xffd0
	v_ashrrev_i32_e32 v3, 31, v2
	v_mul_lo_u32 v4, v7, s4
	v_lshlrev_b64 v[2:3], 12, v[2:3]
	v_add_lshl_u32 v4, v4, v26, 3
	v_lshl_add_u64 v[2:3], s[60:61], 0, v[2:3]
	v_ashrrev_i32_e32 v5, 31, v4
	v_lshl_add_u64 v[2:3], v[4:5], 1, v[2:3]
	global_load_dwordx4 v[2:5], v[2:3], off

.LBB0_776:
	v_readlane_b32 s4, v242, 40
	s_mul_hi_u32 s5, s4, 0xba00
	s_mul_i32 s4, s4, 0xba00
	v_readlane_b32 s6, v243, 54
	s_add_u32 s4, s6, s4
	v_readlane_b32 s6, v243, 55
	s_addc_u32 s5, s6, s5
	v_lshlrev_b32_e32 v54, 4, v0
	s_nop 2
	global_load_dwordx4 v[30:33], v54, s[4:5] offset:-8
	v_add_u32_e32 v55, 0x2000, v54
	global_load_dwordx4 v[34:37], v55, s[4:5] offset:-8
	v_add_u32_e32 v55, 0x4000, v54
	global_load_dwordx4 v[38:41], v55, s[4:5] offset:-8
	v_add_u32_e32 v55, 0x6000, v54
	global_load_dwordx4 v[42:45], v55, s[4:5] offset:-8
	v_add_u32_e32 v55, 0x8000, v54
	global_load_dwordx4 v[46:49], v55, s[4:5] offset:-8
	v_mov_b32_e32 v50, 0
	v_mov_b32_e32 v51, 0
	v_mov_b32_e32 v52, 0
	v_mov_b32_e32 v53, 0
	v_mov_b32_e32 v58, 0
	v_mov_b32_e32 v59, 0
	v_mov_b32_e32 v60, 0
	v_mov_b32_e32 v61, 0
	v_cmp_gt_u32_e32 vcc, 0x1a0, v0
	s_and_saveexec_b64 s[12:13], vcc
	s_cbranch_execz .Lstw_k5
	v_add_u32_e32 v55, 0xa000, v54
	global_load_dwordx4 v[50:53], v55, s[4:5] offset:-8
.Lstw_k5:
	s_or_b64 exec, exec, s[12:13]
	v_mov_b32_e32 v97, 0x2aaaaaab
	v_add_u32_e32 v56, 0x0, v0
	v_mul_hi_u32 v57, v56, v97
	v_lshrrev_b32_e32 v57, 4, v57
	v_mul_u32_u24_e32 v62, 0x60, v57
	v_sub_u32_e32 v56, v56, v62
	v_and_b32_e32 v62, 1, v56
	v_lshl_or_b32 v62, v57, 1, v62
	v_lshrrev_b32_e32 v56, 1, v56
	v_mad_u32_u24 v62, v62, 48, v56
	v_lshl_add_u32 v62, v62, 4, 32
	v_add_u32_e32 v56, 0x200, v0
	v_mul_hi_u32 v57, v56, v97
	v_lshrrev_b32_e32 v57, 4, v57
	v_mul_u32_u24_e32 v63, 0x60, v57
	v_sub_u32_e32 v56, v56, v63
	v_and_b32_e32 v63, 1, v56
	v_lshl_or_b32 v63, v57, 1, v63
	v_lshrrev_b32_e32 v56, 1, v56
	v_mad_u32_u24 v63, v63, 48, v56
	v_lshl_add_u32 v63, v63, 4, 32
	v_add_u32_e32 v56, 0x400, v0
	v_mul_hi_u32 v57, v56, v97
	v_lshrrev_b32_e32 v57, 4, v57
	v_mul_u32_u24_e32 v64, 0x60, v57
	v_sub_u32_e32 v56, v56, v64
	v_and_b32_e32 v64, 1, v56
	v_lshl_or_b32 v64, v57, 1, v64
	v_lshrrev_b32_e32 v56, 1, v56
	v_mad_u32_u24 v64, v64, 48, v56
	v_lshl_add_u32 v64, v64, 4, 32
	v_add_u32_e32 v56, 0x600, v0
	v_mul_hi_u32 v57, v56, v97
	v_lshrrev_b32_e32 v57, 4, v57
	v_mul_u32_u24_e32 v65, 0x60, v57
	v_sub_u32_e32 v56, v56, v65
	v_and_b32_e32 v65, 1, v56
	v_lshl_or_b32 v65, v57, 1, v65
	v_lshrrev_b32_e32 v56, 1, v56
	v_mad_u32_u24 v65, v65, 48, v56
	v_lshl_add_u32 v65, v65, 4, 32
	v_add_u32_e32 v56, 0x800, v0
	v_mul_hi_u32 v57, v56, v97
	v_lshrrev_b32_e32 v57, 4, v57
	v_mul_u32_u24_e32 v94, 0x60, v57
	v_sub_u32_e32 v56, v56, v94
	v_and_b32_e32 v94, 1, v56
	v_lshl_or_b32 v94, v57, 1, v94
	v_lshrrev_b32_e32 v56, 1, v56
	v_mad_u32_u24 v94, v94, 48, v56
	v_lshl_add_u32 v94, v94, 4, 32
	v_add_u32_e32 v56, 0xa00, v0
	v_mul_hi_u32 v57, v56, v97
	v_lshrrev_b32_e32 v57, 4, v57
	v_mul_u32_u24_e32 v95, 0x60, v57
	v_sub_u32_e32 v56, v56, v95
	v_and_b32_e32 v95, 1, v56
	v_lshl_or_b32 v95, v57, 1, v95
	v_lshrrev_b32_e32 v56, 1, v56
	v_mad_u32_u24 v95, v95, 48, v56
	v_lshl_add_u32 v95, v95, 4, 32
	v_add_u32_e32 v56, 0xc00, v0
	v_mul_hi_u32 v57, v56, v97
	v_lshrrev_b32_e32 v57, 4, v57
	v_mul_u32_u24_e32 v96, 0x60, v57
	v_sub_u32_e32 v56, v56, v96
	v_and_b32_e32 v96, 1, v56
	v_lshl_or_b32 v96, v57, 1, v96
	v_lshrrev_b32_e32 v56, 1, v56
	v_mad_u32_u24 v96, v96, 48, v56
	v_lshl_add_u32 v96, v96, 4, 32
	s_waitcnt vmcnt(0)
	ds_write_b128 v62, v[30:33]
	ds_write_b128 v63, v[34:37]
	ds_write_b128 v64, v[38:41]
	ds_write_b128 v65, v[42:45]
	ds_write_b128 v94, v[46:49]
	ds_write_b128 v95, v[50:53]
	v_cmp_gt_u32_e32 vcc, 0x180, v0
	s_and_saveexec_b64 s[12:13], vcc
	ds_write_b128 v96, v[58:61]
	s_or_b64 exec, exec, s[12:13]
	s_andn2_b64 vcc, exec, s[2:3]
	v_readlane_b32 s2, v243, 27
	v_readlane_b32 s3, v243, 28
	s_mov_b32 s23, s21
	s_nop 0
	v_cndmask_b32_e64 v26, 0, 1, s[2:3]
	v_cmp_ne_u32_e64 s[2:3], 1, v26
	s_nop 1
	v_writelane_b32 v242, s2, 51
	s_nop 1
	v_writelane_b32 v242, s3, 52
	s_cbranch_vccnz .LBB0_794
	v_readlane_b32 s2, v242, 51
	v_readlane_b32 s3, v242, 52
	v_readlane_b32 s4, v244, 0
	s_and_b64 vcc, exec, s[2:3]
	v_readlane_b32 s6, v244, 2
	v_readlane_b32 s7, v244, 3
	s_movk_i32 s12, 0x80
	s_movk_i32 s13, 0x70
	s_movk_i32 s14, 0x2000
	s_movk_i32 s16, 0xc0
	s_movk_i32 s17, 0x4000
	s_movk_i32 s30, 0x6000
	s_movk_i32 s31, 0x60
	s_movk_i32 s34, 0x50
	s_movk_i32 s35, 0x90
	s_movk_i32 s36, 0xa0
	s_movk_i32 s37, 0xb0
	s_movk_i32 s42, 0xd0
	s_movk_i32 s43, 0xe0
	s_movk_i32 s94, 0xf0
	s_mov_b32 s22, 0x3b800000
	v_readlane_b32 s5, v244, 1
	s_cbranch_vccnz .LBB0_780
	v_readlane_b32 s10, v242, 0
	v_readlane_b32 s3, v242, 40
	v_readlane_b32 s11, v242, 1
	s_lshl_b32 s4, s3, 8
	s_mov_b32 s5, s11
	s_lshl_b32 s2, s3, 2
	s_lshl_b64 s[4:5], s[4:5], 2
	s_add_u32 s10, s86, s4
	s_addc_u32 s11, s87, s5
	s_add_u32 s40, s88, s4
	s_addc_u32 s41, s89, s5
	v_readlane_b32 s3, v243, 52
	s_mov_b32 s4, s24
